# G1 epilogue: v_permlane16_swap pairs the ni/ni+1 packed bf16 columns so two dwordx2 row stores become one dwordx4 (64-B row segments)
# speedup vs baseline: 1.0028x; 1.0028x over previous
.LBB0_82:
	s_or_b64 exec, exec, s[24:25]
	v_add_u32_e32 v66, s2, v142
	v_lshlrev_b32_e32 v65, 2, v66
	v_and_b32_e32 v65, 0xfffff000, v65
	v_or_b32_e32 v64, s27, v147
	v_add_u32_e32 v65, 0xffff9000, v65
	v_cmp_lt_i32_e32 vcc, s13, v66
	s_waitcnt lgkmcnt(0)
	s_barrier
	v_mbcnt_lo_u32_b32 v196, -1, 0
	v_mbcnt_hi_u32_b32 v196, -1, v196
	v_bfe_u32 v196, v196, 4, 1
	v_mul_u32_u24_e32 v196, 24, v196
	v_mov_b32_e32 v197, 0
	v_cndmask_b32_e32 v128, 0, v65, vcc
	v_ashrrev_i32_e32 v65, 31, v64
	v_lshl_add_u64 v[68:69], v[128:129], 2, s[0:1]
	s_waitcnt vmcnt(6)
	v_lshlrev_b64 v[100:101], 2, v[64:65]
	s_waitcnt vmcnt(3)
	v_lshl_add_u64 v[110:111], v[68:69], 0, v[100:101]
	global_load_dwordx4 v[96:99], v[110:111], off
	v_readlane_b32 s3, v250, 8
	s_add_i32 s3, s26, s3
	s_cmpk_lt_i32 s3, 0xa00
	s_cselect_b32 s24, s3, s26
	s_ashr_i32 s25, s24, 31
	s_lshr_b32 s25, s25, 25
	s_add_i32 s25, s24, s25
	v_ashrrev_i32_e32 v67, 31, v66
	s_ashr_i32 s26, s25, 7
	s_and_b32 s25, s25, 0xffffff80
	v_lshlrev_b64 v[66:67], 13, v[66:67]
	s_sub_i32 s24, s24, s25
	v_lshlrev_b64 v[108:109], 1, v[64:65]
	v_lshl_add_u64 v[64:65], s[30:31], 0, v[66:67]
	s_lshl_b32 s25, s26, 2
	s_and_b32 s26, s24, 3
	s_ashr_i32 s24, s24, 2
	v_lshl_add_u64 v[114:115], v[64:65], 0, v[108:109]
	v_lshl_add_u32 v64, s24, 7, v130
	v_ashrrev_i32_e32 v65, 31, v64
	v_lshlrev_b64 v[64:65], 11, v[64:65]
	v_lshl_add_u64 v[64:65], v[136:137], 0, v[64:65]
	v_add_co_u32_e32 v84, vcc, s11, v64
	s_or_b32 s25, s26, s25
	s_nop 0
	v_addc_co_u32_e32 v85, vcc, 0, v65, vcc
	v_lshl_add_u32 v66, s25, 7, v130
	v_add_co_u32_e32 v72, vcc, s33, v64
	ds_read_b32 v106, v148
	ds_read_b32 v112, v150
	ds_read_b32 v102, v152
	ds_read_b32 v104, v154
	v_ashrrev_i32_e32 v67, 31, v66
	v_addc_co_u32_e32 v73, vcc, 0, v65, vcc
	v_lshlrev_b64 v[66:67], 11, v[66:67]
	v_add_co_u32_e32 v74, vcc, s59, v64
	v_lshl_add_u64 v[66:67], v[134:135], 0, v[66:67]
	s_nop 0
	v_addc_co_u32_e32 v75, vcc, 0, v65, vcc
	v_add_co_u32_e32 v80, vcc, s11, v66
	s_cmpk_gt_i32 s3, 0x9ff
	s_nop 0
	v_addc_co_u32_e32 v81, vcc, 0, v67, vcc
	v_add_co_u32_e32 v82, vcc, s33, v66
	s_mov_b32 s26, s3
	s_nop 0
	v_addc_co_u32_e32 v83, vcc, 0, v67, vcc
	v_add_co_u32_e32 v86, vcc, s59, v66
	s_waitcnt vmcnt(0) lgkmcnt(3)
	v_pk_fma_f32 v[62:63], v[62:63], v[106:107], v[98:99] op_sel_hi:[1,0,1]
	v_pk_fma_f32 v[60:61], v[60:61], v[106:107], v[96:97] op_sel_hi:[1,0,1]
	v_max_f32_e32 v97, 0, v63
	v_max_f32_e32 v96, 0, v61
	v_max_f32_e32 v60, 0, v60
	v_max_f32_e32 v61, 0, v62
	v_pk_mul_f32 v[62:63], v[96:97], v[96:97]
	v_pk_mul_f32 v[60:61], v[60:61], v[60:61]
	v_and_b32_sdwa v98, v63, v170 dst_sel:DWORD dst_unused:UNUSED_PAD src0_sel:WORD_1 src1_sel:DWORD
	v_and_b32_sdwa v99, v62, v170 dst_sel:DWORD dst_unused:UNUSED_PAD src0_sel:WORD_1 src1_sel:DWORD
	v_and_b32_sdwa v96, v61, v170 dst_sel:DWORD dst_unused:UNUSED_PAD src0_sel:WORD_1 src1_sel:DWORD
	v_and_b32_sdwa v97, v60, v170 dst_sel:DWORD dst_unused:UNUSED_PAD src0_sel:WORD_1 src1_sel:DWORD
	v_add3_u32 v63, v63, v98, s56
	v_add3_u32 v62, v62, v99, s56
	v_add3_u32 v60, v60, v97, s56
	v_add3_u32 v61, v61, v96, s56
	v_and_b32_e32 v63, 0xffff0000, v63
	v_and_b32_e32 v62, 0xffff0000, v62
	v_addc_co_u32_e32 v87, vcc, 0, v67, vcc
	v_or_b32_sdwa v61, v63, v61 dst_sel:DWORD dst_unused:UNUSED_PAD src0_sel:DWORD src1_sel:WORD_1
	v_or_b32_sdwa v60, v62, v60 dst_sel:DWORD dst_unused:UNUSED_PAD src0_sel:DWORD src1_sel:WORD_1
	global_load_dwordx4 v[68:71], v[66:67], off
	global_load_dwordx4 v[76:79], v[64:65], off
	global_load_dwordx4 v[88:91], v[72:73], off
	global_load_dwordx4 v[92:95], v[74:75], off
	s_nop 0
	global_load_dwordx4 v[64:67], v[80:81], off
	global_load_dwordx4 v[72:75], v[82:83], off
	s_nop 0
	global_load_dwordx4 v[80:83], v[86:87], off
	s_nop 0
	global_load_dwordx4 v[84:87], v[84:85], off
	s_nop 0
	global_load_dwordx4 v[192:195], v[110:111], off offset:64
	s_waitcnt vmcnt(0)
	v_pk_fma_f32 v[58:59], v[58:59], v[106:107], v[194:195] op_sel_hi:[1,0,1]
	v_pk_fma_f32 v[56:57], v[56:57], v[106:107], v[192:193] op_sel_hi:[1,0,1]
	v_max_f32_e32 v193, 0, v59
	v_max_f32_e32 v192, 0, v57
	v_max_f32_e32 v56, 0, v56
	v_max_f32_e32 v57, 0, v58
	v_pk_mul_f32 v[58:59], v[192:193], v[192:193]
	v_pk_mul_f32 v[56:57], v[56:57], v[56:57]
	v_and_b32_sdwa v194, v59, v170 dst_sel:DWORD dst_unused:UNUSED_PAD src0_sel:WORD_1 src1_sel:DWORD
	v_and_b32_sdwa v195, v58, v170 dst_sel:DWORD dst_unused:UNUSED_PAD src0_sel:WORD_1 src1_sel:DWORD
	v_and_b32_sdwa v192, v57, v170 dst_sel:DWORD dst_unused:UNUSED_PAD src0_sel:WORD_1 src1_sel:DWORD
	v_and_b32_sdwa v193, v56, v170 dst_sel:DWORD dst_unused:UNUSED_PAD src0_sel:WORD_1 src1_sel:DWORD
	v_add3_u32 v59, v59, v194, s56
	v_add3_u32 v58, v58, v195, s56
	v_add3_u32 v56, v56, v193, s56
	v_add3_u32 v57, v57, v192, s56
	v_and_b32_e32 v59, 0xffff0000, v59
	v_and_b32_e32 v58, 0xffff0000, v58
	v_or_b32_sdwa v63, v59, v57 dst_sel:DWORD dst_unused:UNUSED_PAD src0_sel:DWORD src1_sel:WORD_1
	v_or_b32_sdwa v62, v58, v56 dst_sel:DWORD dst_unused:UNUSED_PAD src0_sel:DWORD src1_sel:WORD_1
	v_lshl_add_u64 v[114:115], v[114:115], 0, v[196:197]
	s_nop 1
	v_permlane16_swap_b32_e32 v60, v62
	v_permlane16_swap_b32_e32 v61, v63
	global_store_dwordx4 v[114:115], v[60:63], off
	s_nop 1
	global_load_dwordx4 v[56:59], v[110:111], off offset:128
	s_waitcnt vmcnt(0)
	v_pk_fma_f32 v[54:55], v[54:55], v[106:107], v[58:59] op_sel_hi:[1,0,1]
	v_pk_fma_f32 v[52:53], v[52:53], v[106:107], v[56:57] op_sel_hi:[1,0,1]
	v_max_f32_e32 v57, 0, v55
	v_max_f32_e32 v56, 0, v53
	v_max_f32_e32 v52, 0, v52
	v_max_f32_e32 v53, 0, v54
	v_pk_mul_f32 v[54:55], v[56:57], v[56:57]
	v_pk_mul_f32 v[52:53], v[52:53], v[52:53]
	v_and_b32_sdwa v58, v55, v170 dst_sel:DWORD dst_unused:UNUSED_PAD src0_sel:WORD_1 src1_sel:DWORD
	v_and_b32_sdwa v59, v54, v170 dst_sel:DWORD dst_unused:UNUSED_PAD src0_sel:WORD_1 src1_sel:DWORD
	v_and_b32_sdwa v56, v53, v170 dst_sel:DWORD dst_unused:UNUSED_PAD src0_sel:WORD_1 src1_sel:DWORD
	v_and_b32_sdwa v57, v52, v170 dst_sel:DWORD dst_unused:UNUSED_PAD src0_sel:WORD_1 src1_sel:DWORD
	v_add3_u32 v55, v55, v58, s56
	v_add3_u32 v54, v54, v59, s56
	v_add3_u32 v52, v52, v57, s56
	v_add3_u32 v53, v53, v56, s56
	v_and_b32_e32 v55, 0xffff0000, v55
	v_and_b32_e32 v54, 0xffff0000, v54
	v_or_b32_sdwa v53, v55, v53 dst_sel:DWORD dst_unused:UNUSED_PAD src0_sel:DWORD src1_sel:WORD_1
	v_or_b32_sdwa v52, v54, v52 dst_sel:DWORD dst_unused:UNUSED_PAD src0_sel:DWORD src1_sel:WORD_1
	global_load_dwordx4 v[192:195], v[110:111], off offset:192
	v_add_u32_e32 v56, s2, v149
	v_lshlrev_b32_e32 v57, 2, v56
	v_and_b32_e32 v57, 0xfffff000, v57
	v_add_u32_e32 v57, 0xffff9000, v57
	v_cmp_lt_i32_e32 vcc, s13, v56
	s_waitcnt vmcnt(0)
	v_pk_fma_f32 v[50:51], v[50:51], v[106:107], v[194:195] op_sel_hi:[1,0,1]
	v_pk_fma_f32 v[48:49], v[48:49], v[106:107], v[192:193] op_sel_hi:[1,0,1]
	v_max_f32_e32 v193, 0, v51
	v_max_f32_e32 v192, 0, v49
	v_max_f32_e32 v48, 0, v48
	v_max_f32_e32 v49, 0, v50
	v_pk_mul_f32 v[50:51], v[192:193], v[192:193]
	v_pk_mul_f32 v[48:49], v[48:49], v[48:49]
	v_and_b32_sdwa v194, v51, v170 dst_sel:DWORD dst_unused:UNUSED_PAD src0_sel:WORD_1 src1_sel:DWORD
	v_and_b32_sdwa v195, v50, v170 dst_sel:DWORD dst_unused:UNUSED_PAD src0_sel:WORD_1 src1_sel:DWORD
	v_and_b32_sdwa v192, v49, v170 dst_sel:DWORD dst_unused:UNUSED_PAD src0_sel:WORD_1 src1_sel:DWORD
	v_and_b32_sdwa v193, v48, v170 dst_sel:DWORD dst_unused:UNUSED_PAD src0_sel:WORD_1 src1_sel:DWORD
	v_add3_u32 v51, v51, v194, s56
	v_add3_u32 v50, v50, v195, s56
	v_cndmask_b32_e32 v128, 0, v57, vcc
	v_add3_u32 v48, v48, v193, s56
	v_add3_u32 v49, v49, v192, s56
	v_and_b32_e32 v51, 0xffff0000, v51
	v_and_b32_e32 v50, 0xffff0000, v50
	v_lshl_add_u64 v[58:59], v[128:129], 2, s[0:1]
	v_or_b32_sdwa v55, v51, v49 dst_sel:DWORD dst_unused:UNUSED_PAD src0_sel:DWORD src1_sel:WORD_1
	v_or_b32_sdwa v54, v50, v48 dst_sel:DWORD dst_unused:UNUSED_PAD src0_sel:DWORD src1_sel:WORD_1
	v_lshl_add_u64 v[58:59], v[58:59], 0, v[100:101]
	s_nop 1
	v_permlane16_swap_b32_e32 v52, v54
	v_permlane16_swap_b32_e32 v53, v55
	global_store_dwordx4 v[114:115], v[52:55], off offset:64
	s_nop 1
	global_load_dwordx4 v[48:51], v[58:59], off
	v_ashrrev_i32_e32 v57, 31, v56
	v_lshlrev_b64 v[52:53], 13, v[56:57]
	v_lshl_add_u64 v[52:53], s[30:31], 0, v[52:53]
	v_lshl_add_u64 v[52:53], v[52:53], 0, v[108:109]
	s_waitcnt vmcnt(0) lgkmcnt(2)
	v_pk_fma_f32 v[46:47], v[46:47], v[112:113], v[50:51] op_sel_hi:[1,0,1]
	v_pk_fma_f32 v[44:45], v[44:45], v[112:113], v[48:49] op_sel_hi:[1,0,1]
	v_max_f32_e32 v49, 0, v47
	v_max_f32_e32 v48, 0, v45
	v_max_f32_e32 v44, 0, v44
	v_max_f32_e32 v45, 0, v46
	v_pk_mul_f32 v[46:47], v[48:49], v[48:49]
	v_pk_mul_f32 v[44:45], v[44:45], v[44:45]
	v_and_b32_sdwa v50, v47, v170 dst_sel:DWORD dst_unused:UNUSED_PAD src0_sel:WORD_1 src1_sel:DWORD
	v_and_b32_sdwa v51, v46, v170 dst_sel:DWORD dst_unused:UNUSED_PAD src0_sel:WORD_1 src1_sel:DWORD
	v_and_b32_sdwa v48, v45, v170 dst_sel:DWORD dst_unused:UNUSED_PAD src0_sel:WORD_1 src1_sel:DWORD
	v_and_b32_sdwa v49, v44, v170 dst_sel:DWORD dst_unused:UNUSED_PAD src0_sel:WORD_1 src1_sel:DWORD
	v_add3_u32 v47, v47, v50, s56
	v_add3_u32 v46, v46, v51, s56
	v_add3_u32 v44, v44, v49, s56
	v_add3_u32 v45, v45, v48, s56
	v_and_b32_e32 v47, 0xffff0000, v47
	v_and_b32_e32 v46, 0xffff0000, v46
	v_or_b32_sdwa v45, v47, v45 dst_sel:DWORD dst_unused:UNUSED_PAD src0_sel:DWORD src1_sel:WORD_1
	v_or_b32_sdwa v44, v46, v44 dst_sel:DWORD dst_unused:UNUSED_PAD src0_sel:DWORD src1_sel:WORD_1
	global_load_dwordx4 v[192:195], v[58:59], off offset:64
	s_waitcnt vmcnt(0)
	v_pk_fma_f32 v[42:43], v[42:43], v[112:113], v[194:195] op_sel_hi:[1,0,1]
	v_pk_fma_f32 v[40:41], v[40:41], v[112:113], v[192:193] op_sel_hi:[1,0,1]
	v_max_f32_e32 v193, 0, v43
	v_max_f32_e32 v192, 0, v41
	v_max_f32_e32 v40, 0, v40
	v_max_f32_e32 v41, 0, v42
	v_pk_mul_f32 v[42:43], v[192:193], v[192:193]
	v_pk_mul_f32 v[40:41], v[40:41], v[40:41]
	v_and_b32_sdwa v194, v43, v170 dst_sel:DWORD dst_unused:UNUSED_PAD src0_sel:WORD_1 src1_sel:DWORD
	v_and_b32_sdwa v195, v42, v170 dst_sel:DWORD dst_unused:UNUSED_PAD src0_sel:WORD_1 src1_sel:DWORD
	v_and_b32_sdwa v192, v41, v170 dst_sel:DWORD dst_unused:UNUSED_PAD src0_sel:WORD_1 src1_sel:DWORD
	v_and_b32_sdwa v193, v40, v170 dst_sel:DWORD dst_unused:UNUSED_PAD src0_sel:WORD_1 src1_sel:DWORD
	v_add3_u32 v43, v43, v194, s56
	v_add3_u32 v42, v42, v195, s56
	v_add3_u32 v40, v40, v193, s56
	v_add3_u32 v41, v41, v192, s56
	v_and_b32_e32 v43, 0xffff0000, v43
	v_and_b32_e32 v42, 0xffff0000, v42
	v_or_b32_sdwa v47, v43, v41 dst_sel:DWORD dst_unused:UNUSED_PAD src0_sel:DWORD src1_sel:WORD_1
	v_or_b32_sdwa v46, v42, v40 dst_sel:DWORD dst_unused:UNUSED_PAD src0_sel:DWORD src1_sel:WORD_1
	v_lshl_add_u64 v[52:53], v[52:53], 0, v[196:197]
	s_nop 1
	v_permlane16_swap_b32_e32 v44, v46
	v_permlane16_swap_b32_e32 v45, v47
	global_store_dwordx4 v[52:53], v[44:47], off
	s_nop 1
	global_load_dwordx4 v[40:43], v[58:59], off offset:128
	s_waitcnt vmcnt(0)
	v_pk_fma_f32 v[38:39], v[38:39], v[112:113], v[42:43] op_sel_hi:[1,0,1]
	v_pk_fma_f32 v[36:37], v[36:37], v[112:113], v[40:41] op_sel_hi:[1,0,1]
	v_max_f32_e32 v41, 0, v39
	v_max_f32_e32 v40, 0, v37
	v_max_f32_e32 v36, 0, v36
	v_max_f32_e32 v37, 0, v38
	v_pk_mul_f32 v[38:39], v[40:41], v[40:41]
	v_pk_mul_f32 v[36:37], v[36:37], v[36:37]
	v_and_b32_sdwa v42, v39, v170 dst_sel:DWORD dst_unused:UNUSED_PAD src0_sel:WORD_1 src1_sel:DWORD
	v_and_b32_sdwa v43, v38, v170 dst_sel:DWORD dst_unused:UNUSED_PAD src0_sel:WORD_1 src1_sel:DWORD
	v_and_b32_sdwa v40, v37, v170 dst_sel:DWORD dst_unused:UNUSED_PAD src0_sel:WORD_1 src1_sel:DWORD
	v_and_b32_sdwa v41, v36, v170 dst_sel:DWORD dst_unused:UNUSED_PAD src0_sel:WORD_1 src1_sel:DWORD
	v_add3_u32 v39, v39, v42, s56
	v_add3_u32 v38, v38, v43, s56
	v_add3_u32 v36, v36, v41, s56
	v_add3_u32 v37, v37, v40, s56
	v_and_b32_e32 v39, 0xffff0000, v39
	v_and_b32_e32 v38, 0xffff0000, v38
	v_or_b32_sdwa v37, v39, v37 dst_sel:DWORD dst_unused:UNUSED_PAD src0_sel:DWORD src1_sel:WORD_1
	v_or_b32_sdwa v36, v38, v36 dst_sel:DWORD dst_unused:UNUSED_PAD src0_sel:DWORD src1_sel:WORD_1
	global_load_dwordx4 v[192:195], v[58:59], off offset:192
	v_add_u32_e32 v40, s2, v151
	v_lshlrev_b32_e32 v41, 2, v40
	v_and_b32_e32 v41, 0xfffff000, v41
	v_add_u32_e32 v41, 0xffff9000, v41
	v_cmp_lt_i32_e32 vcc, s13, v40
	s_waitcnt vmcnt(0)
	v_pk_fma_f32 v[34:35], v[34:35], v[112:113], v[194:195] op_sel_hi:[1,0,1]
	v_pk_fma_f32 v[32:33], v[32:33], v[112:113], v[192:193] op_sel_hi:[1,0,1]
	v_max_f32_e32 v193, 0, v35
	v_max_f32_e32 v192, 0, v33
	v_max_f32_e32 v32, 0, v32
	v_max_f32_e32 v33, 0, v34
	v_pk_mul_f32 v[34:35], v[192:193], v[192:193]
	v_pk_mul_f32 v[32:33], v[32:33], v[32:33]
	v_and_b32_sdwa v194, v35, v170 dst_sel:DWORD dst_unused:UNUSED_PAD src0_sel:WORD_1 src1_sel:DWORD
	v_and_b32_sdwa v195, v34, v170 dst_sel:DWORD dst_unused:UNUSED_PAD src0_sel:WORD_1 src1_sel:DWORD
	v_and_b32_sdwa v192, v33, v170 dst_sel:DWORD dst_unused:UNUSED_PAD src0_sel:WORD_1 src1_sel:DWORD
	v_and_b32_sdwa v193, v32, v170 dst_sel:DWORD dst_unused:UNUSED_PAD src0_sel:WORD_1 src1_sel:DWORD
	v_add3_u32 v35, v35, v194, s56
	v_add3_u32 v34, v34, v195, s56
	v_cndmask_b32_e32 v128, 0, v41, vcc
	v_add3_u32 v32, v32, v193, s56
	v_add3_u32 v33, v33, v192, s56
	v_and_b32_e32 v35, 0xffff0000, v35
	v_and_b32_e32 v34, 0xffff0000, v34
	v_lshl_add_u64 v[42:43], v[128:129], 2, s[0:1]
	v_or_b32_sdwa v39, v35, v33 dst_sel:DWORD dst_unused:UNUSED_PAD src0_sel:DWORD src1_sel:WORD_1
	v_or_b32_sdwa v38, v34, v32 dst_sel:DWORD dst_unused:UNUSED_PAD src0_sel:DWORD src1_sel:WORD_1
	v_lshl_add_u64 v[42:43], v[42:43], 0, v[100:101]
	s_nop 1
	v_permlane16_swap_b32_e32 v36, v38
	v_permlane16_swap_b32_e32 v37, v39
	global_store_dwordx4 v[52:53], v[36:39], off offset:64
	s_nop 1
	global_load_dwordx4 v[34:37], v[42:43], off
	v_ashrrev_i32_e32 v41, 31, v40
	v_lshlrev_b64 v[32:33], 13, v[40:41]
	v_lshl_add_u64 v[32:33], s[30:31], 0, v[32:33]
	v_lshl_add_u64 v[32:33], v[32:33], 0, v[108:109]
	s_waitcnt vmcnt(0) lgkmcnt(1)
	v_pk_fma_f32 v[30:31], v[30:31], v[102:103], v[36:37] op_sel_hi:[1,0,1]
	v_pk_fma_f32 v[28:29], v[28:29], v[102:103], v[34:35] op_sel_hi:[1,0,1]
	v_max_f32_e32 v35, 0, v31
	v_max_f32_e32 v34, 0, v29
	v_max_f32_e32 v28, 0, v28
	v_max_f32_e32 v29, 0, v30
	v_pk_mul_f32 v[30:31], v[34:35], v[34:35]
	v_pk_mul_f32 v[28:29], v[28:29], v[28:29]
	v_and_b32_sdwa v36, v31, v170 dst_sel:DWORD dst_unused:UNUSED_PAD src0_sel:WORD_1 src1_sel:DWORD
	v_and_b32_sdwa v37, v30, v170 dst_sel:DWORD dst_unused:UNUSED_PAD src0_sel:WORD_1 src1_sel:DWORD
	v_and_b32_sdwa v34, v29, v170 dst_sel:DWORD dst_unused:UNUSED_PAD src0_sel:WORD_1 src1_sel:DWORD
	v_and_b32_sdwa v35, v28, v170 dst_sel:DWORD dst_unused:UNUSED_PAD src0_sel:WORD_1 src1_sel:DWORD
	v_add3_u32 v31, v31, v36, s56
	v_add3_u32 v30, v30, v37, s56
	v_add3_u32 v28, v28, v35, s56
	v_add3_u32 v29, v29, v34, s56
	v_and_b32_e32 v31, 0xffff0000, v31
	v_and_b32_e32 v30, 0xffff0000, v30
	v_or_b32_sdwa v29, v31, v29 dst_sel:DWORD dst_unused:UNUSED_PAD src0_sel:DWORD src1_sel:WORD_1
	v_or_b32_sdwa v28, v30, v28 dst_sel:DWORD dst_unused:UNUSED_PAD src0_sel:DWORD src1_sel:WORD_1
	global_load_dwordx4 v[192:195], v[42:43], off offset:64
	s_waitcnt vmcnt(0)
	v_pk_fma_f32 v[26:27], v[26:27], v[102:103], v[194:195] op_sel_hi:[1,0,1]
	v_pk_fma_f32 v[24:25], v[24:25], v[102:103], v[192:193] op_sel_hi:[1,0,1]
	v_max_f32_e32 v193, 0, v27
	v_max_f32_e32 v192, 0, v25
	v_max_f32_e32 v24, 0, v24
	v_max_f32_e32 v25, 0, v26
	v_pk_mul_f32 v[26:27], v[192:193], v[192:193]
	v_pk_mul_f32 v[24:25], v[24:25], v[24:25]
	v_and_b32_sdwa v194, v27, v170 dst_sel:DWORD dst_unused:UNUSED_PAD src0_sel:WORD_1 src1_sel:DWORD
	v_and_b32_sdwa v195, v26, v170 dst_sel:DWORD dst_unused:UNUSED_PAD src0_sel:WORD_1 src1_sel:DWORD
	v_and_b32_sdwa v192, v25, v170 dst_sel:DWORD dst_unused:UNUSED_PAD src0_sel:WORD_1 src1_sel:DWORD
	v_and_b32_sdwa v193, v24, v170 dst_sel:DWORD dst_unused:UNUSED_PAD src0_sel:WORD_1 src1_sel:DWORD
	v_add3_u32 v27, v27, v194, s56
	v_add3_u32 v26, v26, v195, s56
	v_add3_u32 v24, v24, v193, s56
	v_add3_u32 v25, v25, v192, s56
	v_and_b32_e32 v27, 0xffff0000, v27
	v_and_b32_e32 v26, 0xffff0000, v26
	v_or_b32_sdwa v31, v27, v25 dst_sel:DWORD dst_unused:UNUSED_PAD src0_sel:DWORD src1_sel:WORD_1
	v_or_b32_sdwa v30, v26, v24 dst_sel:DWORD dst_unused:UNUSED_PAD src0_sel:DWORD src1_sel:WORD_1
	v_lshl_add_u64 v[32:33], v[32:33], 0, v[196:197]
	s_nop 1
	v_permlane16_swap_b32_e32 v28, v30
	v_permlane16_swap_b32_e32 v29, v31
	global_store_dwordx4 v[32:33], v[28:31], off
	s_nop 1
	global_load_dwordx4 v[24:27], v[42:43], off offset:128
	s_waitcnt vmcnt(0)
	v_pk_fma_f32 v[22:23], v[22:23], v[102:103], v[26:27] op_sel_hi:[1,0,1]
	v_pk_fma_f32 v[20:21], v[20:21], v[102:103], v[24:25] op_sel_hi:[1,0,1]
	v_max_f32_e32 v25, 0, v23
	v_max_f32_e32 v24, 0, v21
	v_max_f32_e32 v20, 0, v20
	v_max_f32_e32 v21, 0, v22
	v_pk_mul_f32 v[22:23], v[24:25], v[24:25]
	v_pk_mul_f32 v[20:21], v[20:21], v[20:21]
	v_and_b32_sdwa v26, v23, v170 dst_sel:DWORD dst_unused:UNUSED_PAD src0_sel:WORD_1 src1_sel:DWORD
	v_and_b32_sdwa v27, v22, v170 dst_sel:DWORD dst_unused:UNUSED_PAD src0_sel:WORD_1 src1_sel:DWORD
	v_and_b32_sdwa v24, v21, v170 dst_sel:DWORD dst_unused:UNUSED_PAD src0_sel:WORD_1 src1_sel:DWORD
	v_and_b32_sdwa v25, v20, v170 dst_sel:DWORD dst_unused:UNUSED_PAD src0_sel:WORD_1 src1_sel:DWORD
	v_add3_u32 v23, v23, v26, s56
	v_add3_u32 v22, v22, v27, s56
	v_add3_u32 v20, v20, v25, s56
	v_add3_u32 v21, v21, v24, s56
	v_and_b32_e32 v23, 0xffff0000, v23
	v_and_b32_e32 v22, 0xffff0000, v22
	v_or_b32_sdwa v21, v23, v21 dst_sel:DWORD dst_unused:UNUSED_PAD src0_sel:DWORD src1_sel:WORD_1
	v_or_b32_sdwa v20, v22, v20 dst_sel:DWORD dst_unused:UNUSED_PAD src0_sel:DWORD src1_sel:WORD_1
	global_load_dwordx4 v[192:195], v[42:43], off offset:192
	v_add_u32_e32 v24, s2, v153
	v_lshlrev_b32_e32 v25, 2, v24
	v_and_b32_e32 v25, 0xfffff000, v25
	v_add_u32_e32 v25, 0xffff9000, v25
	v_cmp_lt_i32_e32 vcc, s13, v24
	s_waitcnt vmcnt(0)
	v_pk_fma_f32 v[18:19], v[18:19], v[102:103], v[194:195] op_sel_hi:[1,0,1]
	v_pk_fma_f32 v[16:17], v[16:17], v[102:103], v[192:193] op_sel_hi:[1,0,1]
	v_max_f32_e32 v193, 0, v19
	v_max_f32_e32 v192, 0, v17
	v_max_f32_e32 v16, 0, v16
	v_max_f32_e32 v17, 0, v18
	v_pk_mul_f32 v[18:19], v[192:193], v[192:193]
	v_pk_mul_f32 v[16:17], v[16:17], v[16:17]
	v_and_b32_sdwa v194, v19, v170 dst_sel:DWORD dst_unused:UNUSED_PAD src0_sel:WORD_1 src1_sel:DWORD
	v_and_b32_sdwa v195, v18, v170 dst_sel:DWORD dst_unused:UNUSED_PAD src0_sel:WORD_1 src1_sel:DWORD
	v_and_b32_sdwa v192, v17, v170 dst_sel:DWORD dst_unused:UNUSED_PAD src0_sel:WORD_1 src1_sel:DWORD
	v_and_b32_sdwa v193, v16, v170 dst_sel:DWORD dst_unused:UNUSED_PAD src0_sel:WORD_1 src1_sel:DWORD
	v_add3_u32 v19, v19, v194, s56
	v_add3_u32 v18, v18, v195, s56
	v_cndmask_b32_e32 v128, 0, v25, vcc
	v_add3_u32 v16, v16, v193, s56
	v_add3_u32 v17, v17, v192, s56
	v_and_b32_e32 v19, 0xffff0000, v19
	v_and_b32_e32 v18, 0xffff0000, v18
	v_lshl_add_u64 v[26:27], v[128:129], 2, s[0:1]
	v_or_b32_sdwa v23, v19, v17 dst_sel:DWORD dst_unused:UNUSED_PAD src0_sel:DWORD src1_sel:WORD_1
	v_or_b32_sdwa v22, v18, v16 dst_sel:DWORD dst_unused:UNUSED_PAD src0_sel:DWORD src1_sel:WORD_1
	v_lshl_add_u64 v[26:27], v[26:27], 0, v[100:101]
	s_nop 1
	v_permlane16_swap_b32_e32 v20, v22
	v_permlane16_swap_b32_e32 v21, v23
	global_store_dwordx4 v[32:33], v[20:23], off offset:64
	s_nop 1
	global_load_dwordx4 v[16:19], v[26:27], off
	v_ashrrev_i32_e32 v25, 31, v24
	v_lshlrev_b64 v[20:21], 13, v[24:25]
	v_lshl_add_u64 v[20:21], s[30:31], 0, v[20:21]
	v_lshl_add_u64 v[20:21], v[20:21], 0, v[108:109]
	s_waitcnt vmcnt(0) lgkmcnt(0)
	v_pk_fma_f32 v[14:15], v[14:15], v[104:105], v[18:19] op_sel_hi:[1,0,1]
	v_pk_fma_f32 v[12:13], v[12:13], v[104:105], v[16:17] op_sel_hi:[1,0,1]
	v_max_f32_e32 v17, 0, v15
	v_max_f32_e32 v16, 0, v13
	v_max_f32_e32 v12, 0, v12
	v_max_f32_e32 v13, 0, v14
	v_pk_mul_f32 v[14:15], v[16:17], v[16:17]
	v_pk_mul_f32 v[12:13], v[12:13], v[12:13]
	v_and_b32_sdwa v18, v15, v170 dst_sel:DWORD dst_unused:UNUSED_PAD src0_sel:WORD_1 src1_sel:DWORD
	v_and_b32_sdwa v19, v14, v170 dst_sel:DWORD dst_unused:UNUSED_PAD src0_sel:WORD_1 src1_sel:DWORD
	v_and_b32_sdwa v16, v13, v170 dst_sel:DWORD dst_unused:UNUSED_PAD src0_sel:WORD_1 src1_sel:DWORD
	v_and_b32_sdwa v17, v12, v170 dst_sel:DWORD dst_unused:UNUSED_PAD src0_sel:WORD_1 src1_sel:DWORD
	v_add3_u32 v15, v15, v18, s56
	v_add3_u32 v14, v14, v19, s56
	v_add3_u32 v12, v12, v17, s56
	v_add3_u32 v13, v13, v16, s56
	v_and_b32_e32 v15, 0xffff0000, v15
	v_and_b32_e32 v14, 0xffff0000, v14
	v_or_b32_sdwa v13, v15, v13 dst_sel:DWORD dst_unused:UNUSED_PAD src0_sel:DWORD src1_sel:WORD_1
	v_or_b32_sdwa v12, v14, v12 dst_sel:DWORD dst_unused:UNUSED_PAD src0_sel:DWORD src1_sel:WORD_1
	global_load_dwordx4 v[192:195], v[26:27], off offset:64
	s_waitcnt vmcnt(0)
	v_pk_fma_f32 v[10:11], v[10:11], v[104:105], v[194:195] op_sel_hi:[1,0,1]
	v_pk_fma_f32 v[8:9], v[8:9], v[104:105], v[192:193] op_sel_hi:[1,0,1]
	v_max_f32_e32 v193, 0, v11
	v_max_f32_e32 v192, 0, v9
	v_max_f32_e32 v8, 0, v8
	v_max_f32_e32 v9, 0, v10
	v_pk_mul_f32 v[10:11], v[192:193], v[192:193]
	v_pk_mul_f32 v[8:9], v[8:9], v[8:9]
	v_and_b32_sdwa v194, v11, v170 dst_sel:DWORD dst_unused:UNUSED_PAD src0_sel:WORD_1 src1_sel:DWORD
	v_and_b32_sdwa v195, v10, v170 dst_sel:DWORD dst_unused:UNUSED_PAD src0_sel:WORD_1 src1_sel:DWORD
	v_and_b32_sdwa v192, v9, v170 dst_sel:DWORD dst_unused:UNUSED_PAD src0_sel:WORD_1 src1_sel:DWORD
	v_and_b32_sdwa v193, v8, v170 dst_sel:DWORD dst_unused:UNUSED_PAD src0_sel:WORD_1 src1_sel:DWORD
	v_add3_u32 v11, v11, v194, s56
	v_add3_u32 v10, v10, v195, s56
	v_add3_u32 v8, v8, v193, s56
	v_add3_u32 v9, v9, v192, s56
	v_and_b32_e32 v11, 0xffff0000, v11
	v_and_b32_e32 v10, 0xffff0000, v10
	v_or_b32_sdwa v15, v11, v9 dst_sel:DWORD dst_unused:UNUSED_PAD src0_sel:DWORD src1_sel:WORD_1
	v_or_b32_sdwa v14, v10, v8 dst_sel:DWORD dst_unused:UNUSED_PAD src0_sel:DWORD src1_sel:WORD_1
	v_lshl_add_u64 v[20:21], v[20:21], 0, v[196:197]
	s_nop 1
	v_permlane16_swap_b32_e32 v12, v14
	v_permlane16_swap_b32_e32 v13, v15
	global_store_dwordx4 v[20:21], v[12:15], off
	s_nop 1
	global_load_dwordx4 v[8:11], v[26:27], off offset:128
	s_waitcnt vmcnt(0)
	v_pk_fma_f32 v[6:7], v[6:7], v[104:105], v[10:11] op_sel_hi:[1,0,1]
	v_pk_fma_f32 v[4:5], v[4:5], v[104:105], v[8:9] op_sel_hi:[1,0,1]
	v_max_f32_e32 v9, 0, v7
	v_max_f32_e32 v8, 0, v5
	v_max_f32_e32 v4, 0, v4
	v_max_f32_e32 v5, 0, v6
	v_pk_mul_f32 v[6:7], v[8:9], v[8:9]
	v_pk_mul_f32 v[4:5], v[4:5], v[4:5]
	v_and_b32_sdwa v10, v7, v170 dst_sel:DWORD dst_unused:UNUSED_PAD src0_sel:WORD_1 src1_sel:DWORD
	v_and_b32_sdwa v11, v6, v170 dst_sel:DWORD dst_unused:UNUSED_PAD src0_sel:WORD_1 src1_sel:DWORD
	v_and_b32_sdwa v8, v5, v170 dst_sel:DWORD dst_unused:UNUSED_PAD src0_sel:WORD_1 src1_sel:DWORD
	v_and_b32_sdwa v9, v4, v170 dst_sel:DWORD dst_unused:UNUSED_PAD src0_sel:WORD_1 src1_sel:DWORD
	v_add3_u32 v7, v7, v10, s56
	v_add3_u32 v6, v6, v11, s56
	v_add3_u32 v4, v4, v9, s56
	v_add3_u32 v5, v5, v8, s56
	v_and_b32_e32 v7, 0xffff0000, v7
	v_and_b32_e32 v6, 0xffff0000, v6
	v_or_b32_sdwa v5, v7, v5 dst_sel:DWORD dst_unused:UNUSED_PAD src0_sel:DWORD src1_sel:WORD_1
	v_or_b32_sdwa v4, v6, v4 dst_sel:DWORD dst_unused:UNUSED_PAD src0_sel:DWORD src1_sel:WORD_1
	global_load_dwordx4 v[192:195], v[26:27], off offset:192
	s_waitcnt vmcnt(0)
	v_pk_fma_f32 v[2:3], v[2:3], v[104:105], v[194:195] op_sel_hi:[1,0,1]
	v_pk_fma_f32 v[0:1], v[0:1], v[104:105], v[192:193] op_sel_hi:[1,0,1]
	v_max_f32_e32 v193, 0, v3
	v_max_f32_e32 v192, 0, v1
	v_max_f32_e32 v0, 0, v0
	v_max_f32_e32 v1, 0, v2
	v_pk_mul_f32 v[2:3], v[192:193], v[192:193]
	v_pk_mul_f32 v[0:1], v[0:1], v[0:1]
	v_and_b32_sdwa v194, v3, v170 dst_sel:DWORD dst_unused:UNUSED_PAD src0_sel:WORD_1 src1_sel:DWORD
	v_and_b32_sdwa v195, v2, v170 dst_sel:DWORD dst_unused:UNUSED_PAD src0_sel:WORD_1 src1_sel:DWORD
	v_and_b32_sdwa v192, v1, v170 dst_sel:DWORD dst_unused:UNUSED_PAD src0_sel:WORD_1 src1_sel:DWORD
	v_and_b32_sdwa v193, v0, v170 dst_sel:DWORD dst_unused:UNUSED_PAD src0_sel:WORD_1 src1_sel:DWORD
	v_add3_u32 v3, v3, v194, s56
	v_add3_u32 v2, v2, v195, s56
	v_add3_u32 v0, v0, v193, s56
	v_add3_u32 v1, v1, v192, s56
	v_and_b32_e32 v3, 0xffff0000, v3
	v_and_b32_e32 v2, 0xffff0000, v2
	v_or_b32_sdwa v7, v3, v1 dst_sel:DWORD dst_unused:UNUSED_PAD src0_sel:DWORD src1_sel:WORD_1
	v_or_b32_sdwa v6, v2, v0 dst_sel:DWORD dst_unused:UNUSED_PAD src0_sel:DWORD src1_sel:WORD_1
	s_nop 1
	v_permlane16_swap_b32_e32 v4, v6
	v_permlane16_swap_b32_e32 v5, v7
	global_store_dwordx4 v[20:21], v[4:7], off offset:64
	s_nop 1
	s_cbranch_scc1 .LBB0_87

.LBB0_382:
	s_or_b64 exec, exec, s[24:25]
	v_add_u32_e32 v66, s2, v142
	v_lshlrev_b32_e32 v65, 2, v66
	v_and_b32_e32 v65, 0xfffff000, v65
	v_or_b32_e32 v64, s29, v147
	v_add_u32_e32 v65, 0xffff9000, v65
	v_cmp_lt_i32_e32 vcc, s13, v66
	s_waitcnt lgkmcnt(0)
	s_barrier
	v_mbcnt_lo_u32_b32 v196, -1, 0
	v_mbcnt_hi_u32_b32 v196, -1, v196
	v_bfe_u32 v196, v196, 4, 1
	v_mul_u32_u24_e32 v196, 24, v196
	v_mov_b32_e32 v197, 0
	v_cndmask_b32_e32 v128, 0, v65, vcc
	v_ashrrev_i32_e32 v65, 31, v64
	v_lshl_add_u64 v[68:69], v[128:129], 2, s[0:1]
	s_waitcnt vmcnt(6)
	v_lshlrev_b64 v[100:101], 2, v[64:65]
	s_waitcnt vmcnt(3)
	v_lshl_add_u64 v[110:111], v[68:69], 0, v[100:101]
	global_load_dwordx4 v[96:99], v[110:111], off
	v_readlane_b32 s3, v250, 8
	s_add_i32 s3, s28, s3
	s_cmpk_lt_i32 s3, 0xa00
	s_cselect_b32 s24, s3, s28
	s_ashr_i32 s25, s24, 31
	s_lshr_b32 s25, s25, 25
	s_add_i32 s25, s24, s25
	v_ashrrev_i32_e32 v67, 31, v66
	s_ashr_i32 s28, s25, 7
	s_and_b32 s25, s25, 0xffffff80
	v_lshlrev_b64 v[66:67], 13, v[66:67]
	s_sub_i32 s24, s24, s25
	v_lshlrev_b64 v[108:109], 1, v[64:65]
	v_lshl_add_u64 v[64:65], s[30:31], 0, v[66:67]
	s_lshl_b32 s25, s28, 2
	s_and_b32 s28, s24, 3
	s_ashr_i32 s24, s24, 2
	v_lshl_add_u64 v[114:115], v[64:65], 0, v[108:109]
	v_lshl_add_u32 v64, s24, 7, v130
	v_ashrrev_i32_e32 v65, 31, v64
	v_lshlrev_b64 v[64:65], 11, v[64:65]
	v_lshl_add_u64 v[64:65], v[136:137], 0, v[64:65]
	v_add_co_u32_e32 v84, vcc, s11, v64
	s_or_b32 s25, s28, s25
	s_nop 0
	v_addc_co_u32_e32 v85, vcc, 0, v65, vcc
	v_lshl_add_u32 v66, s25, 7, v130
	v_add_co_u32_e32 v72, vcc, s33, v64
	ds_read_b32 v106, v148
	ds_read_b32 v112, v150
	ds_read_b32 v102, v152
	ds_read_b32 v104, v154
	v_ashrrev_i32_e32 v67, 31, v66
	v_addc_co_u32_e32 v73, vcc, 0, v65, vcc
	v_lshlrev_b64 v[66:67], 11, v[66:67]
	v_add_co_u32_e32 v74, vcc, s59, v64
	v_lshl_add_u64 v[66:67], v[134:135], 0, v[66:67]
	s_nop 0
	v_addc_co_u32_e32 v75, vcc, 0, v65, vcc
	v_add_co_u32_e32 v80, vcc, s11, v66
	s_cmpk_gt_i32 s3, 0x9ff
	s_nop 0
	v_addc_co_u32_e32 v81, vcc, 0, v67, vcc
	v_add_co_u32_e32 v82, vcc, s33, v66
	s_mov_b32 s28, s3
	s_nop 0
	v_addc_co_u32_e32 v83, vcc, 0, v67, vcc
	v_add_co_u32_e32 v86, vcc, s59, v66
	s_waitcnt vmcnt(0) lgkmcnt(3)
	v_pk_fma_f32 v[62:63], v[62:63], v[106:107], v[98:99] op_sel_hi:[1,0,1]
	v_pk_fma_f32 v[60:61], v[60:61], v[106:107], v[96:97] op_sel_hi:[1,0,1]
	v_max_f32_e32 v97, 0, v63
	v_max_f32_e32 v96, 0, v61
	v_max_f32_e32 v60, 0, v60
	v_max_f32_e32 v61, 0, v62
	v_pk_mul_f32 v[62:63], v[96:97], v[96:97]
	v_pk_mul_f32 v[60:61], v[60:61], v[60:61]
	v_and_b32_sdwa v98, v63, v170 dst_sel:DWORD dst_unused:UNUSED_PAD src0_sel:WORD_1 src1_sel:DWORD
	v_and_b32_sdwa v99, v62, v170 dst_sel:DWORD dst_unused:UNUSED_PAD src0_sel:WORD_1 src1_sel:DWORD
	v_and_b32_sdwa v96, v61, v170 dst_sel:DWORD dst_unused:UNUSED_PAD src0_sel:WORD_1 src1_sel:DWORD
	v_and_b32_sdwa v97, v60, v170 dst_sel:DWORD dst_unused:UNUSED_PAD src0_sel:WORD_1 src1_sel:DWORD
	v_add3_u32 v63, v63, v98, s56
	v_add3_u32 v62, v62, v99, s56
	v_add3_u32 v60, v60, v97, s56
	v_add3_u32 v61, v61, v96, s56
	v_and_b32_e32 v63, 0xffff0000, v63
	v_and_b32_e32 v62, 0xffff0000, v62
	v_addc_co_u32_e32 v87, vcc, 0, v67, vcc
	v_or_b32_sdwa v61, v63, v61 dst_sel:DWORD dst_unused:UNUSED_PAD src0_sel:DWORD src1_sel:WORD_1
	v_or_b32_sdwa v60, v62, v60 dst_sel:DWORD dst_unused:UNUSED_PAD src0_sel:DWORD src1_sel:WORD_1
	global_load_dwordx4 v[68:71], v[66:67], off
	global_load_dwordx4 v[76:79], v[64:65], off
	global_load_dwordx4 v[88:91], v[72:73], off
	global_load_dwordx4 v[92:95], v[74:75], off
	s_nop 0
	global_load_dwordx4 v[64:67], v[80:81], off
	global_load_dwordx4 v[72:75], v[82:83], off
	s_nop 0
	global_load_dwordx4 v[80:83], v[86:87], off
	s_nop 0
	global_load_dwordx4 v[84:87], v[84:85], off
	s_nop 0
	global_load_dwordx4 v[192:195], v[110:111], off offset:64
	s_waitcnt vmcnt(0)
	v_pk_fma_f32 v[58:59], v[58:59], v[106:107], v[194:195] op_sel_hi:[1,0,1]
	v_pk_fma_f32 v[56:57], v[56:57], v[106:107], v[192:193] op_sel_hi:[1,0,1]
	v_max_f32_e32 v193, 0, v59
	v_max_f32_e32 v192, 0, v57
	v_max_f32_e32 v56, 0, v56
	v_max_f32_e32 v57, 0, v58
	v_pk_mul_f32 v[58:59], v[192:193], v[192:193]
	v_pk_mul_f32 v[56:57], v[56:57], v[56:57]
	v_and_b32_sdwa v194, v59, v170 dst_sel:DWORD dst_unused:UNUSED_PAD src0_sel:WORD_1 src1_sel:DWORD
	v_and_b32_sdwa v195, v58, v170 dst_sel:DWORD dst_unused:UNUSED_PAD src0_sel:WORD_1 src1_sel:DWORD
	v_and_b32_sdwa v192, v57, v170 dst_sel:DWORD dst_unused:UNUSED_PAD src0_sel:WORD_1 src1_sel:DWORD
	v_and_b32_sdwa v193, v56, v170 dst_sel:DWORD dst_unused:UNUSED_PAD src0_sel:WORD_1 src1_sel:DWORD
	v_add3_u32 v59, v59, v194, s56
	v_add3_u32 v58, v58, v195, s56
	v_add3_u32 v56, v56, v193, s56
	v_add3_u32 v57, v57, v192, s56
	v_and_b32_e32 v59, 0xffff0000, v59
	v_and_b32_e32 v58, 0xffff0000, v58
	v_or_b32_sdwa v63, v59, v57 dst_sel:DWORD dst_unused:UNUSED_PAD src0_sel:DWORD src1_sel:WORD_1
	v_or_b32_sdwa v62, v58, v56 dst_sel:DWORD dst_unused:UNUSED_PAD src0_sel:DWORD src1_sel:WORD_1
	v_lshl_add_u64 v[114:115], v[114:115], 0, v[196:197]
	s_nop 1
	v_permlane16_swap_b32_e32 v60, v62
	v_permlane16_swap_b32_e32 v61, v63
	global_store_dwordx4 v[114:115], v[60:63], off
	s_nop 1
	global_load_dwordx4 v[56:59], v[110:111], off offset:128
	s_waitcnt vmcnt(0)
	v_pk_fma_f32 v[54:55], v[54:55], v[106:107], v[58:59] op_sel_hi:[1,0,1]
	v_pk_fma_f32 v[52:53], v[52:53], v[106:107], v[56:57] op_sel_hi:[1,0,1]
	v_max_f32_e32 v57, 0, v55
	v_max_f32_e32 v56, 0, v53
	v_max_f32_e32 v52, 0, v52
	v_max_f32_e32 v53, 0, v54
	v_pk_mul_f32 v[54:55], v[56:57], v[56:57]
	v_pk_mul_f32 v[52:53], v[52:53], v[52:53]
	v_and_b32_sdwa v58, v55, v170 dst_sel:DWORD dst_unused:UNUSED_PAD src0_sel:WORD_1 src1_sel:DWORD
	v_and_b32_sdwa v59, v54, v170 dst_sel:DWORD dst_unused:UNUSED_PAD src0_sel:WORD_1 src1_sel:DWORD
	v_and_b32_sdwa v56, v53, v170 dst_sel:DWORD dst_unused:UNUSED_PAD src0_sel:WORD_1 src1_sel:DWORD
	v_and_b32_sdwa v57, v52, v170 dst_sel:DWORD dst_unused:UNUSED_PAD src0_sel:WORD_1 src1_sel:DWORD
	v_add3_u32 v55, v55, v58, s56
	v_add3_u32 v54, v54, v59, s56
	v_add3_u32 v52, v52, v57, s56
	v_add3_u32 v53, v53, v56, s56
	v_and_b32_e32 v55, 0xffff0000, v55
	v_and_b32_e32 v54, 0xffff0000, v54
	v_or_b32_sdwa v53, v55, v53 dst_sel:DWORD dst_unused:UNUSED_PAD src0_sel:DWORD src1_sel:WORD_1
	v_or_b32_sdwa v52, v54, v52 dst_sel:DWORD dst_unused:UNUSED_PAD src0_sel:DWORD src1_sel:WORD_1
	global_load_dwordx4 v[192:195], v[110:111], off offset:192
	v_add_u32_e32 v56, s2, v149
	v_lshlrev_b32_e32 v57, 2, v56
	v_and_b32_e32 v57, 0xfffff000, v57
	v_add_u32_e32 v57, 0xffff9000, v57
	v_cmp_lt_i32_e32 vcc, s13, v56
	s_waitcnt vmcnt(0)
	v_pk_fma_f32 v[50:51], v[50:51], v[106:107], v[194:195] op_sel_hi:[1,0,1]
	v_pk_fma_f32 v[48:49], v[48:49], v[106:107], v[192:193] op_sel_hi:[1,0,1]
	v_max_f32_e32 v193, 0, v51
	v_max_f32_e32 v192, 0, v49
	v_max_f32_e32 v48, 0, v48
	v_max_f32_e32 v49, 0, v50
	v_pk_mul_f32 v[50:51], v[192:193], v[192:193]
	v_pk_mul_f32 v[48:49], v[48:49], v[48:49]
	v_and_b32_sdwa v194, v51, v170 dst_sel:DWORD dst_unused:UNUSED_PAD src0_sel:WORD_1 src1_sel:DWORD
	v_and_b32_sdwa v195, v50, v170 dst_sel:DWORD dst_unused:UNUSED_PAD src0_sel:WORD_1 src1_sel:DWORD
	v_and_b32_sdwa v192, v49, v170 dst_sel:DWORD dst_unused:UNUSED_PAD src0_sel:WORD_1 src1_sel:DWORD
	v_and_b32_sdwa v193, v48, v170 dst_sel:DWORD dst_unused:UNUSED_PAD src0_sel:WORD_1 src1_sel:DWORD
	v_add3_u32 v51, v51, v194, s56
	v_add3_u32 v50, v50, v195, s56
	v_cndmask_b32_e32 v128, 0, v57, vcc
	v_add3_u32 v48, v48, v193, s56
	v_add3_u32 v49, v49, v192, s56
	v_and_b32_e32 v51, 0xffff0000, v51
	v_and_b32_e32 v50, 0xffff0000, v50
	v_lshl_add_u64 v[58:59], v[128:129], 2, s[0:1]
	v_or_b32_sdwa v55, v51, v49 dst_sel:DWORD dst_unused:UNUSED_PAD src0_sel:DWORD src1_sel:WORD_1
	v_or_b32_sdwa v54, v50, v48 dst_sel:DWORD dst_unused:UNUSED_PAD src0_sel:DWORD src1_sel:WORD_1
	v_lshl_add_u64 v[58:59], v[58:59], 0, v[100:101]
	s_nop 1
	v_permlane16_swap_b32_e32 v52, v54
	v_permlane16_swap_b32_e32 v53, v55
	global_store_dwordx4 v[114:115], v[52:55], off offset:64
	s_nop 1
	global_load_dwordx4 v[48:51], v[58:59], off
	v_ashrrev_i32_e32 v57, 31, v56
	v_lshlrev_b64 v[52:53], 13, v[56:57]
	v_lshl_add_u64 v[52:53], s[30:31], 0, v[52:53]
	v_lshl_add_u64 v[52:53], v[52:53], 0, v[108:109]
	s_waitcnt vmcnt(0) lgkmcnt(2)
	v_pk_fma_f32 v[46:47], v[46:47], v[112:113], v[50:51] op_sel_hi:[1,0,1]
	v_pk_fma_f32 v[44:45], v[44:45], v[112:113], v[48:49] op_sel_hi:[1,0,1]
	v_max_f32_e32 v49, 0, v47
	v_max_f32_e32 v48, 0, v45
	v_max_f32_e32 v44, 0, v44
	v_max_f32_e32 v45, 0, v46
	v_pk_mul_f32 v[46:47], v[48:49], v[48:49]
	v_pk_mul_f32 v[44:45], v[44:45], v[44:45]
	v_and_b32_sdwa v50, v47, v170 dst_sel:DWORD dst_unused:UNUSED_PAD src0_sel:WORD_1 src1_sel:DWORD
	v_and_b32_sdwa v51, v46, v170 dst_sel:DWORD dst_unused:UNUSED_PAD src0_sel:WORD_1 src1_sel:DWORD
	v_and_b32_sdwa v48, v45, v170 dst_sel:DWORD dst_unused:UNUSED_PAD src0_sel:WORD_1 src1_sel:DWORD
	v_and_b32_sdwa v49, v44, v170 dst_sel:DWORD dst_unused:UNUSED_PAD src0_sel:WORD_1 src1_sel:DWORD
	v_add3_u32 v47, v47, v50, s56
	v_add3_u32 v46, v46, v51, s56
	v_add3_u32 v44, v44, v49, s56
	v_add3_u32 v45, v45, v48, s56
	v_and_b32_e32 v47, 0xffff0000, v47
	v_and_b32_e32 v46, 0xffff0000, v46
	v_or_b32_sdwa v45, v47, v45 dst_sel:DWORD dst_unused:UNUSED_PAD src0_sel:DWORD src1_sel:WORD_1
	v_or_b32_sdwa v44, v46, v44 dst_sel:DWORD dst_unused:UNUSED_PAD src0_sel:DWORD src1_sel:WORD_1
	global_load_dwordx4 v[192:195], v[58:59], off offset:64
	s_waitcnt vmcnt(0)
	v_pk_fma_f32 v[42:43], v[42:43], v[112:113], v[194:195] op_sel_hi:[1,0,1]
	v_pk_fma_f32 v[40:41], v[40:41], v[112:113], v[192:193] op_sel_hi:[1,0,1]
	v_max_f32_e32 v193, 0, v43
	v_max_f32_e32 v192, 0, v41
	v_max_f32_e32 v40, 0, v40
	v_max_f32_e32 v41, 0, v42
	v_pk_mul_f32 v[42:43], v[192:193], v[192:193]
	v_pk_mul_f32 v[40:41], v[40:41], v[40:41]
	v_and_b32_sdwa v194, v43, v170 dst_sel:DWORD dst_unused:UNUSED_PAD src0_sel:WORD_1 src1_sel:DWORD
	v_and_b32_sdwa v195, v42, v170 dst_sel:DWORD dst_unused:UNUSED_PAD src0_sel:WORD_1 src1_sel:DWORD
	v_and_b32_sdwa v192, v41, v170 dst_sel:DWORD dst_unused:UNUSED_PAD src0_sel:WORD_1 src1_sel:DWORD
	v_and_b32_sdwa v193, v40, v170 dst_sel:DWORD dst_unused:UNUSED_PAD src0_sel:WORD_1 src1_sel:DWORD
	v_add3_u32 v43, v43, v194, s56
	v_add3_u32 v42, v42, v195, s56
	v_add3_u32 v40, v40, v193, s56
	v_add3_u32 v41, v41, v192, s56
	v_and_b32_e32 v43, 0xffff0000, v43
	v_and_b32_e32 v42, 0xffff0000, v42
	v_or_b32_sdwa v47, v43, v41 dst_sel:DWORD dst_unused:UNUSED_PAD src0_sel:DWORD src1_sel:WORD_1
	v_or_b32_sdwa v46, v42, v40 dst_sel:DWORD dst_unused:UNUSED_PAD src0_sel:DWORD src1_sel:WORD_1
	v_lshl_add_u64 v[52:53], v[52:53], 0, v[196:197]
	s_nop 1
	v_permlane16_swap_b32_e32 v44, v46
	v_permlane16_swap_b32_e32 v45, v47
	global_store_dwordx4 v[52:53], v[44:47], off
	s_nop 1
	global_load_dwordx4 v[40:43], v[58:59], off offset:128
	s_waitcnt vmcnt(0)
	v_pk_fma_f32 v[38:39], v[38:39], v[112:113], v[42:43] op_sel_hi:[1,0,1]
	v_pk_fma_f32 v[36:37], v[36:37], v[112:113], v[40:41] op_sel_hi:[1,0,1]
	v_max_f32_e32 v41, 0, v39
	v_max_f32_e32 v40, 0, v37
	v_max_f32_e32 v36, 0, v36
	v_max_f32_e32 v37, 0, v38
	v_pk_mul_f32 v[38:39], v[40:41], v[40:41]
	v_pk_mul_f32 v[36:37], v[36:37], v[36:37]
	v_and_b32_sdwa v42, v39, v170 dst_sel:DWORD dst_unused:UNUSED_PAD src0_sel:WORD_1 src1_sel:DWORD
	v_and_b32_sdwa v43, v38, v170 dst_sel:DWORD dst_unused:UNUSED_PAD src0_sel:WORD_1 src1_sel:DWORD
	v_and_b32_sdwa v40, v37, v170 dst_sel:DWORD dst_unused:UNUSED_PAD src0_sel:WORD_1 src1_sel:DWORD
	v_and_b32_sdwa v41, v36, v170 dst_sel:DWORD dst_unused:UNUSED_PAD src0_sel:WORD_1 src1_sel:DWORD
	v_add3_u32 v39, v39, v42, s56
	v_add3_u32 v38, v38, v43, s56
	v_add3_u32 v36, v36, v41, s56
	v_add3_u32 v37, v37, v40, s56
	v_and_b32_e32 v39, 0xffff0000, v39
	v_and_b32_e32 v38, 0xffff0000, v38
	v_or_b32_sdwa v37, v39, v37 dst_sel:DWORD dst_unused:UNUSED_PAD src0_sel:DWORD src1_sel:WORD_1
	v_or_b32_sdwa v36, v38, v36 dst_sel:DWORD dst_unused:UNUSED_PAD src0_sel:DWORD src1_sel:WORD_1
	global_load_dwordx4 v[192:195], v[58:59], off offset:192
	v_add_u32_e32 v40, s2, v151
	v_lshlrev_b32_e32 v41, 2, v40
	v_and_b32_e32 v41, 0xfffff000, v41
	v_add_u32_e32 v41, 0xffff9000, v41
	v_cmp_lt_i32_e32 vcc, s13, v40
	s_waitcnt vmcnt(0)
	v_pk_fma_f32 v[34:35], v[34:35], v[112:113], v[194:195] op_sel_hi:[1,0,1]
	v_pk_fma_f32 v[32:33], v[32:33], v[112:113], v[192:193] op_sel_hi:[1,0,1]
	v_max_f32_e32 v193, 0, v35
	v_max_f32_e32 v192, 0, v33
	v_max_f32_e32 v32, 0, v32
	v_max_f32_e32 v33, 0, v34
	v_pk_mul_f32 v[34:35], v[192:193], v[192:193]
	v_pk_mul_f32 v[32:33], v[32:33], v[32:33]
	v_and_b32_sdwa v194, v35, v170 dst_sel:DWORD dst_unused:UNUSED_PAD src0_sel:WORD_1 src1_sel:DWORD
	v_and_b32_sdwa v195, v34, v170 dst_sel:DWORD dst_unused:UNUSED_PAD src0_sel:WORD_1 src1_sel:DWORD
	v_and_b32_sdwa v192, v33, v170 dst_sel:DWORD dst_unused:UNUSED_PAD src0_sel:WORD_1 src1_sel:DWORD
	v_and_b32_sdwa v193, v32, v170 dst_sel:DWORD dst_unused:UNUSED_PAD src0_sel:WORD_1 src1_sel:DWORD
	v_add3_u32 v35, v35, v194, s56
	v_add3_u32 v34, v34, v195, s56
	v_cndmask_b32_e32 v128, 0, v41, vcc
	v_add3_u32 v32, v32, v193, s56
	v_add3_u32 v33, v33, v192, s56
	v_and_b32_e32 v35, 0xffff0000, v35
	v_and_b32_e32 v34, 0xffff0000, v34
	v_lshl_add_u64 v[42:43], v[128:129], 2, s[0:1]
	v_or_b32_sdwa v39, v35, v33 dst_sel:DWORD dst_unused:UNUSED_PAD src0_sel:DWORD src1_sel:WORD_1
	v_or_b32_sdwa v38, v34, v32 dst_sel:DWORD dst_unused:UNUSED_PAD src0_sel:DWORD src1_sel:WORD_1
	v_lshl_add_u64 v[42:43], v[42:43], 0, v[100:101]
	s_nop 1
	v_permlane16_swap_b32_e32 v36, v38
	v_permlane16_swap_b32_e32 v37, v39
	global_store_dwordx4 v[52:53], v[36:39], off offset:64
	s_nop 1
	global_load_dwordx4 v[34:37], v[42:43], off
	v_ashrrev_i32_e32 v41, 31, v40
	v_lshlrev_b64 v[32:33], 13, v[40:41]
	v_lshl_add_u64 v[32:33], s[30:31], 0, v[32:33]
	v_lshl_add_u64 v[32:33], v[32:33], 0, v[108:109]
	s_waitcnt vmcnt(0) lgkmcnt(1)
	v_pk_fma_f32 v[30:31], v[30:31], v[102:103], v[36:37] op_sel_hi:[1,0,1]
	v_pk_fma_f32 v[28:29], v[28:29], v[102:103], v[34:35] op_sel_hi:[1,0,1]
	v_max_f32_e32 v35, 0, v31
	v_max_f32_e32 v34, 0, v29
	v_max_f32_e32 v28, 0, v28
	v_max_f32_e32 v29, 0, v30
	v_pk_mul_f32 v[30:31], v[34:35], v[34:35]
	v_pk_mul_f32 v[28:29], v[28:29], v[28:29]
	v_and_b32_sdwa v36, v31, v170 dst_sel:DWORD dst_unused:UNUSED_PAD src0_sel:WORD_1 src1_sel:DWORD
	v_and_b32_sdwa v37, v30, v170 dst_sel:DWORD dst_unused:UNUSED_PAD src0_sel:WORD_1 src1_sel:DWORD
	v_and_b32_sdwa v34, v29, v170 dst_sel:DWORD dst_unused:UNUSED_PAD src0_sel:WORD_1 src1_sel:DWORD
	v_and_b32_sdwa v35, v28, v170 dst_sel:DWORD dst_unused:UNUSED_PAD src0_sel:WORD_1 src1_sel:DWORD
	v_add3_u32 v31, v31, v36, s56
	v_add3_u32 v30, v30, v37, s56
	v_add3_u32 v28, v28, v35, s56
	v_add3_u32 v29, v29, v34, s56
	v_and_b32_e32 v31, 0xffff0000, v31
	v_and_b32_e32 v30, 0xffff0000, v30
	v_or_b32_sdwa v29, v31, v29 dst_sel:DWORD dst_unused:UNUSED_PAD src0_sel:DWORD src1_sel:WORD_1
	v_or_b32_sdwa v28, v30, v28 dst_sel:DWORD dst_unused:UNUSED_PAD src0_sel:DWORD src1_sel:WORD_1
	global_load_dwordx4 v[192:195], v[42:43], off offset:64
	s_waitcnt vmcnt(0)
	v_pk_fma_f32 v[26:27], v[26:27], v[102:103], v[194:195] op_sel_hi:[1,0,1]
	v_pk_fma_f32 v[24:25], v[24:25], v[102:103], v[192:193] op_sel_hi:[1,0,1]
	v_max_f32_e32 v193, 0, v27
	v_max_f32_e32 v192, 0, v25
	v_max_f32_e32 v24, 0, v24
	v_max_f32_e32 v25, 0, v26
	v_pk_mul_f32 v[26:27], v[192:193], v[192:193]
	v_pk_mul_f32 v[24:25], v[24:25], v[24:25]
	v_and_b32_sdwa v194, v27, v170 dst_sel:DWORD dst_unused:UNUSED_PAD src0_sel:WORD_1 src1_sel:DWORD
	v_and_b32_sdwa v195, v26, v170 dst_sel:DWORD dst_unused:UNUSED_PAD src0_sel:WORD_1 src1_sel:DWORD
	v_and_b32_sdwa v192, v25, v170 dst_sel:DWORD dst_unused:UNUSED_PAD src0_sel:WORD_1 src1_sel:DWORD
	v_and_b32_sdwa v193, v24, v170 dst_sel:DWORD dst_unused:UNUSED_PAD src0_sel:WORD_1 src1_sel:DWORD
	v_add3_u32 v27, v27, v194, s56
	v_add3_u32 v26, v26, v195, s56
	v_add3_u32 v24, v24, v193, s56
	v_add3_u32 v25, v25, v192, s56
	v_and_b32_e32 v27, 0xffff0000, v27
	v_and_b32_e32 v26, 0xffff0000, v26
	v_or_b32_sdwa v31, v27, v25 dst_sel:DWORD dst_unused:UNUSED_PAD src0_sel:DWORD src1_sel:WORD_1
	v_or_b32_sdwa v30, v26, v24 dst_sel:DWORD dst_unused:UNUSED_PAD src0_sel:DWORD src1_sel:WORD_1
	v_lshl_add_u64 v[32:33], v[32:33], 0, v[196:197]
	s_nop 1
	v_permlane16_swap_b32_e32 v28, v30
	v_permlane16_swap_b32_e32 v29, v31
	global_store_dwordx4 v[32:33], v[28:31], off
	s_nop 1
	global_load_dwordx4 v[24:27], v[42:43], off offset:128
	s_waitcnt vmcnt(0)
	v_pk_fma_f32 v[22:23], v[22:23], v[102:103], v[26:27] op_sel_hi:[1,0,1]
	v_pk_fma_f32 v[20:21], v[20:21], v[102:103], v[24:25] op_sel_hi:[1,0,1]
	v_max_f32_e32 v25, 0, v23
	v_max_f32_e32 v24, 0, v21
	v_max_f32_e32 v20, 0, v20
	v_max_f32_e32 v21, 0, v22
	v_pk_mul_f32 v[22:23], v[24:25], v[24:25]
	v_pk_mul_f32 v[20:21], v[20:21], v[20:21]
	v_and_b32_sdwa v26, v23, v170 dst_sel:DWORD dst_unused:UNUSED_PAD src0_sel:WORD_1 src1_sel:DWORD
	v_and_b32_sdwa v27, v22, v170 dst_sel:DWORD dst_unused:UNUSED_PAD src0_sel:WORD_1 src1_sel:DWORD
	v_and_b32_sdwa v24, v21, v170 dst_sel:DWORD dst_unused:UNUSED_PAD src0_sel:WORD_1 src1_sel:DWORD
	v_and_b32_sdwa v25, v20, v170 dst_sel:DWORD dst_unused:UNUSED_PAD src0_sel:WORD_1 src1_sel:DWORD
	v_add3_u32 v23, v23, v26, s56
	v_add3_u32 v22, v22, v27, s56
	v_add3_u32 v20, v20, v25, s56
	v_add3_u32 v21, v21, v24, s56
	v_and_b32_e32 v23, 0xffff0000, v23
	v_and_b32_e32 v22, 0xffff0000, v22
	v_or_b32_sdwa v21, v23, v21 dst_sel:DWORD dst_unused:UNUSED_PAD src0_sel:DWORD src1_sel:WORD_1
	v_or_b32_sdwa v20, v22, v20 dst_sel:DWORD dst_unused:UNUSED_PAD src0_sel:DWORD src1_sel:WORD_1
	global_load_dwordx4 v[192:195], v[42:43], off offset:192
	v_add_u32_e32 v24, s2, v153
	v_lshlrev_b32_e32 v25, 2, v24
	v_and_b32_e32 v25, 0xfffff000, v25
	v_add_u32_e32 v25, 0xffff9000, v25
	v_cmp_lt_i32_e32 vcc, s13, v24
	s_waitcnt vmcnt(0)
	v_pk_fma_f32 v[18:19], v[18:19], v[102:103], v[194:195] op_sel_hi:[1,0,1]
	v_pk_fma_f32 v[16:17], v[16:17], v[102:103], v[192:193] op_sel_hi:[1,0,1]
	v_max_f32_e32 v193, 0, v19
	v_max_f32_e32 v192, 0, v17
	v_max_f32_e32 v16, 0, v16
	v_max_f32_e32 v17, 0, v18
	v_pk_mul_f32 v[18:19], v[192:193], v[192:193]
	v_pk_mul_f32 v[16:17], v[16:17], v[16:17]
	v_and_b32_sdwa v194, v19, v170 dst_sel:DWORD dst_unused:UNUSED_PAD src0_sel:WORD_1 src1_sel:DWORD
	v_and_b32_sdwa v195, v18, v170 dst_sel:DWORD dst_unused:UNUSED_PAD src0_sel:WORD_1 src1_sel:DWORD
	v_and_b32_sdwa v192, v17, v170 dst_sel:DWORD dst_unused:UNUSED_PAD src0_sel:WORD_1 src1_sel:DWORD
	v_and_b32_sdwa v193, v16, v170 dst_sel:DWORD dst_unused:UNUSED_PAD src0_sel:WORD_1 src1_sel:DWORD
	v_add3_u32 v19, v19, v194, s56
	v_add3_u32 v18, v18, v195, s56
	v_cndmask_b32_e32 v128, 0, v25, vcc
	v_add3_u32 v16, v16, v193, s56
	v_add3_u32 v17, v17, v192, s56
	v_and_b32_e32 v19, 0xffff0000, v19
	v_and_b32_e32 v18, 0xffff0000, v18
	v_lshl_add_u64 v[26:27], v[128:129], 2, s[0:1]
	v_or_b32_sdwa v23, v19, v17 dst_sel:DWORD dst_unused:UNUSED_PAD src0_sel:DWORD src1_sel:WORD_1
	v_or_b32_sdwa v22, v18, v16 dst_sel:DWORD dst_unused:UNUSED_PAD src0_sel:DWORD src1_sel:WORD_1
	v_lshl_add_u64 v[26:27], v[26:27], 0, v[100:101]
	s_nop 1
	v_permlane16_swap_b32_e32 v20, v22
	v_permlane16_swap_b32_e32 v21, v23
	global_store_dwordx4 v[32:33], v[20:23], off offset:64
	s_nop 1
	global_load_dwordx4 v[16:19], v[26:27], off
	v_ashrrev_i32_e32 v25, 31, v24
	v_lshlrev_b64 v[20:21], 13, v[24:25]
	v_lshl_add_u64 v[20:21], s[30:31], 0, v[20:21]
	v_lshl_add_u64 v[20:21], v[20:21], 0, v[108:109]
	s_waitcnt vmcnt(0) lgkmcnt(0)
	v_pk_fma_f32 v[14:15], v[14:15], v[104:105], v[18:19] op_sel_hi:[1,0,1]
	v_pk_fma_f32 v[12:13], v[12:13], v[104:105], v[16:17] op_sel_hi:[1,0,1]
	v_max_f32_e32 v17, 0, v15
	v_max_f32_e32 v16, 0, v13
	v_max_f32_e32 v12, 0, v12
	v_max_f32_e32 v13, 0, v14
	v_pk_mul_f32 v[14:15], v[16:17], v[16:17]
	v_pk_mul_f32 v[12:13], v[12:13], v[12:13]
	v_and_b32_sdwa v18, v15, v170 dst_sel:DWORD dst_unused:UNUSED_PAD src0_sel:WORD_1 src1_sel:DWORD
	v_and_b32_sdwa v19, v14, v170 dst_sel:DWORD dst_unused:UNUSED_PAD src0_sel:WORD_1 src1_sel:DWORD
	v_and_b32_sdwa v16, v13, v170 dst_sel:DWORD dst_unused:UNUSED_PAD src0_sel:WORD_1 src1_sel:DWORD
	v_and_b32_sdwa v17, v12, v170 dst_sel:DWORD dst_unused:UNUSED_PAD src0_sel:WORD_1 src1_sel:DWORD
	v_add3_u32 v15, v15, v18, s56
	v_add3_u32 v14, v14, v19, s56
	v_add3_u32 v12, v12, v17, s56
	v_add3_u32 v13, v13, v16, s56
	v_and_b32_e32 v15, 0xffff0000, v15
	v_and_b32_e32 v14, 0xffff0000, v14
	v_or_b32_sdwa v13, v15, v13 dst_sel:DWORD dst_unused:UNUSED_PAD src0_sel:DWORD src1_sel:WORD_1
	v_or_b32_sdwa v12, v14, v12 dst_sel:DWORD dst_unused:UNUSED_PAD src0_sel:DWORD src1_sel:WORD_1
	global_load_dwordx4 v[192:195], v[26:27], off offset:64
	s_waitcnt vmcnt(0)
	v_pk_fma_f32 v[10:11], v[10:11], v[104:105], v[194:195] op_sel_hi:[1,0,1]
	v_pk_fma_f32 v[8:9], v[8:9], v[104:105], v[192:193] op_sel_hi:[1,0,1]
	v_max_f32_e32 v193, 0, v11
	v_max_f32_e32 v192, 0, v9
	v_max_f32_e32 v8, 0, v8
	v_max_f32_e32 v9, 0, v10
	v_pk_mul_f32 v[10:11], v[192:193], v[192:193]
	v_pk_mul_f32 v[8:9], v[8:9], v[8:9]
	v_and_b32_sdwa v194, v11, v170 dst_sel:DWORD dst_unused:UNUSED_PAD src0_sel:WORD_1 src1_sel:DWORD
	v_and_b32_sdwa v195, v10, v170 dst_sel:DWORD dst_unused:UNUSED_PAD src0_sel:WORD_1 src1_sel:DWORD
	v_and_b32_sdwa v192, v9, v170 dst_sel:DWORD dst_unused:UNUSED_PAD src0_sel:WORD_1 src1_sel:DWORD
	v_and_b32_sdwa v193, v8, v170 dst_sel:DWORD dst_unused:UNUSED_PAD src0_sel:WORD_1 src1_sel:DWORD
	v_add3_u32 v11, v11, v194, s56
	v_add3_u32 v10, v10, v195, s56
	v_add3_u32 v8, v8, v193, s56
	v_add3_u32 v9, v9, v192, s56
	v_and_b32_e32 v11, 0xffff0000, v11
	v_and_b32_e32 v10, 0xffff0000, v10
	v_or_b32_sdwa v15, v11, v9 dst_sel:DWORD dst_unused:UNUSED_PAD src0_sel:DWORD src1_sel:WORD_1
	v_or_b32_sdwa v14, v10, v8 dst_sel:DWORD dst_unused:UNUSED_PAD src0_sel:DWORD src1_sel:WORD_1
	v_lshl_add_u64 v[20:21], v[20:21], 0, v[196:197]
	s_nop 1
	v_permlane16_swap_b32_e32 v12, v14
	v_permlane16_swap_b32_e32 v13, v15
	global_store_dwordx4 v[20:21], v[12:15], off
	s_nop 1
	global_load_dwordx4 v[8:11], v[26:27], off offset:128
	s_waitcnt vmcnt(0)
	v_pk_fma_f32 v[6:7], v[6:7], v[104:105], v[10:11] op_sel_hi:[1,0,1]
	v_pk_fma_f32 v[4:5], v[4:5], v[104:105], v[8:9] op_sel_hi:[1,0,1]
	v_max_f32_e32 v9, 0, v7
	v_max_f32_e32 v8, 0, v5
	v_max_f32_e32 v4, 0, v4
	v_max_f32_e32 v5, 0, v6
	v_pk_mul_f32 v[6:7], v[8:9], v[8:9]
	v_pk_mul_f32 v[4:5], v[4:5], v[4:5]
	v_and_b32_sdwa v10, v7, v170 dst_sel:DWORD dst_unused:UNUSED_PAD src0_sel:WORD_1 src1_sel:DWORD
	v_and_b32_sdwa v11, v6, v170 dst_sel:DWORD dst_unused:UNUSED_PAD src0_sel:WORD_1 src1_sel:DWORD
	v_and_b32_sdwa v8, v5, v170 dst_sel:DWORD dst_unused:UNUSED_PAD src0_sel:WORD_1 src1_sel:DWORD
	v_and_b32_sdwa v9, v4, v170 dst_sel:DWORD dst_unused:UNUSED_PAD src0_sel:WORD_1 src1_sel:DWORD
	v_add3_u32 v7, v7, v10, s56
	v_add3_u32 v6, v6, v11, s56
	v_add3_u32 v4, v4, v9, s56
	v_add3_u32 v5, v5, v8, s56
	v_and_b32_e32 v7, 0xffff0000, v7
	v_and_b32_e32 v6, 0xffff0000, v6
	v_or_b32_sdwa v5, v7, v5 dst_sel:DWORD dst_unused:UNUSED_PAD src0_sel:DWORD src1_sel:WORD_1
	v_or_b32_sdwa v4, v6, v4 dst_sel:DWORD dst_unused:UNUSED_PAD src0_sel:DWORD src1_sel:WORD_1
	global_load_dwordx4 v[192:195], v[26:27], off offset:192
	s_waitcnt vmcnt(0)
	v_pk_fma_f32 v[2:3], v[2:3], v[104:105], v[194:195] op_sel_hi:[1,0,1]
	v_pk_fma_f32 v[0:1], v[0:1], v[104:105], v[192:193] op_sel_hi:[1,0,1]
	v_max_f32_e32 v193, 0, v3
	v_max_f32_e32 v192, 0, v1
	v_max_f32_e32 v0, 0, v0
	v_max_f32_e32 v1, 0, v2
	v_pk_mul_f32 v[2:3], v[192:193], v[192:193]
	v_pk_mul_f32 v[0:1], v[0:1], v[0:1]
	v_and_b32_sdwa v194, v3, v170 dst_sel:DWORD dst_unused:UNUSED_PAD src0_sel:WORD_1 src1_sel:DWORD
	v_and_b32_sdwa v195, v2, v170 dst_sel:DWORD dst_unused:UNUSED_PAD src0_sel:WORD_1 src1_sel:DWORD
	v_and_b32_sdwa v192, v1, v170 dst_sel:DWORD dst_unused:UNUSED_PAD src0_sel:WORD_1 src1_sel:DWORD
	v_and_b32_sdwa v193, v0, v170 dst_sel:DWORD dst_unused:UNUSED_PAD src0_sel:WORD_1 src1_sel:DWORD
	v_add3_u32 v3, v3, v194, s56
	v_add3_u32 v2, v2, v195, s56
	v_add3_u32 v0, v0, v193, s56
	v_add3_u32 v1, v1, v192, s56
	v_and_b32_e32 v3, 0xffff0000, v3
	v_and_b32_e32 v2, 0xffff0000, v2
	v_or_b32_sdwa v7, v3, v1 dst_sel:DWORD dst_unused:UNUSED_PAD src0_sel:DWORD src1_sel:WORD_1
	v_or_b32_sdwa v6, v2, v0 dst_sel:DWORD dst_unused:UNUSED_PAD src0_sel:DWORD src1_sel:WORD_1
	s_nop 1
	v_permlane16_swap_b32_e32 v4, v6
	v_permlane16_swap_b32_e32 v5, v7
	global_store_dwordx4 v[20:21], v[4:7], off offset:64
	s_nop 1
	s_cbranch_scc1 .LBB0_388
